# EpiLora decay written as exp(-e^-0.5*sigmoid(x)) (exact identity for exp(-exp(-softplus(-x)-0.5))): 6 instr/elt instead of ~26, on top of gelu trim
# speedup vs baseline: 1.0091x; 1.0091x over previous
;     __device__ __forceinline__ void operator()(f32x4 (&acc)[2][2][4][2], const Unit& u, int wr, int wc, int fr_, int fq_) const {
;     ...
;                         f32x4 v0 = acc[ai][bj][m][0] + b0, v1 = acc[ai][bj][m][1] + b1;
;                         if (kind == 0) {
; #pragma unroll
;                             for (int i = 0; i < 4; ++i) { float z = -v0[i]; float sp = fmaxf(z, 0.f) + __logf(1.0f + __expf(-fabsf(z))); v0[i] = __expf(-__expf(-sp - 0.5f));
;                                                           z = -v1[i]; sp = fmaxf(z, 0.f) + __logf(1.0f + __expf(-fabsf(z))); v1[i] = __expf(-__expf(-sp - 0.5f)); }
;                             *(f32x4*)(DEC + off) = v0; *(f32x4*)(DEC + off + 4) = v1;
.LBB0_927:
	s_andn2_b64 vcc, exec, s[0:1]
	s_cbranch_vccnz .LBB0_929
	v_lshl_add_u64 v[162:163], v[162:163], 2, s[36:37]
	v_mul_f32_e32 v170, 0xbfb8aa3b, v170
	v_mul_f32_e32 v171, 0xbfb8aa3b, v171
	v_mul_f32_e32 v172, 0xbfb8aa3b, v166
	v_mul_f32_e32 v173, 0xbfb8aa3b, v167
	v_mul_f32_e32 v174, 0xbfb8aa3b, v168
	v_mul_f32_e32 v175, 0xbfb8aa3b, v169
	v_mul_f32_e32 v176, 0xbfb8aa3b, v164
	v_mul_f32_e32 v177, 0xbfb8aa3b, v165
	v_exp_f32_e32 v170, v170
	v_exp_f32_e32 v171, v171
	v_exp_f32_e32 v172, v172
	v_exp_f32_e32 v173, v173
	v_exp_f32_e32 v174, v174
	v_exp_f32_e32 v175, v175
	v_exp_f32_e32 v176, v176
	v_exp_f32_e32 v177, v177
	v_add_f32_e32 v170, 1.0, v170
	v_add_f32_e32 v171, 1.0, v171
	v_add_f32_e32 v172, 1.0, v172
	v_add_f32_e32 v173, 1.0, v173
	v_add_f32_e32 v174, 1.0, v174
	v_add_f32_e32 v175, 1.0, v175
	v_add_f32_e32 v176, 1.0, v176
	v_add_f32_e32 v177, 1.0, v177
	v_rcp_f32_e32 v170, v170
	v_rcp_f32_e32 v171, v171
	v_rcp_f32_e32 v172, v172
	v_rcp_f32_e32 v173, v173
	v_rcp_f32_e32 v174, v174
	v_rcp_f32_e32 v175, v175
	v_rcp_f32_e32 v176, v176
	v_rcp_f32_e32 v177, v177
	v_mul_f32_e32 v170, 0xbf60028b, v170
	v_mul_f32_e32 v171, 0xbf60028b, v171
	v_mul_f32_e32 v172, 0xbf60028b, v172
	v_mul_f32_e32 v173, 0xbf60028b, v173
	v_mul_f32_e32 v174, 0xbf60028b, v174
	v_mul_f32_e32 v175, 0xbf60028b, v175
	v_mul_f32_e32 v176, 0xbf60028b, v176
	v_mul_f32_e32 v177, 0xbf60028b, v177
	v_exp_f32_e32 v170, v170
	v_exp_f32_e32 v171, v171
	v_exp_f32_e32 v172, v172
	v_exp_f32_e32 v173, v173
	v_exp_f32_e32 v174, v174
	v_exp_f32_e32 v175, v175
	v_exp_f32_e32 v176, v176
	v_exp_f32_e32 v177, v177
	s_nop 0
	global_store_dwordx4 v[162:163], v[170:173], off
	global_store_dwordx4 v[162:163], v[174:177], off offset:16

;     __device__ __forceinline__ void operator()(f32x4 (&acc)[2][2][4][2], const Unit& u, int wr, int wc, int fr_, int fq_) const {
;     ...
;                     for (int m = 0; m < 4; ++m) { const size_t off = (size_t)(row0 + ai * HALF + m * 16) * 1024 + col0 + bj * HALF;
;                         f32x4 v0 = acc[ai][bj][m][0] + b0, v1 = acc[ai][bj][m][1] + b1;
;                         if (kind == 0) {
; #pragma unroll
;                             for (int i = 0; i < 4; ++i) { float z = -v0[i]; float sp = fmaxf(z, 0.f) + __logf(1.0f + __expf(-fabsf(z))); v0[i] = __expf(-__expf(-sp - 0.5f));
;                                                           z = -v1[i]; sp = fmaxf(z, 0.f) + __logf(1.0f + __expf(-fabsf(z))); v1[i] = __expf(-__expf(-sp - 0.5f)); }
;                             *(f32x4*)(DEC + off) = v0; *(f32x4*)(DEC + off + 4) = v1;
.LBB0_931:
	s_andn2_b64 vcc, exec, s[0:1]
	s_cbranch_vccnz .LBB0_933
	v_lshl_add_u64 v[164:165], v[164:165], 2, s[36:37]
	v_mul_f32_e32 v172, 0xbfb8aa3b, v172
	v_mul_f32_e32 v173, 0xbfb8aa3b, v173
	v_mul_f32_e32 v174, 0xbfb8aa3b, v168
	v_mul_f32_e32 v175, 0xbfb8aa3b, v169
	v_mul_f32_e32 v176, 0xbfb8aa3b, v170
	v_mul_f32_e32 v177, 0xbfb8aa3b, v171
	v_mul_f32_e32 v178, 0xbfb8aa3b, v166
	v_mul_f32_e32 v179, 0xbfb8aa3b, v167
	v_exp_f32_e32 v172, v172
	v_exp_f32_e32 v173, v173
	v_exp_f32_e32 v174, v174
	v_exp_f32_e32 v175, v175
	v_exp_f32_e32 v176, v176
	v_exp_f32_e32 v177, v177
	v_exp_f32_e32 v178, v178
	v_exp_f32_e32 v179, v179
	v_add_f32_e32 v172, 1.0, v172
	v_add_f32_e32 v173, 1.0, v173
	v_add_f32_e32 v174, 1.0, v174
	v_add_f32_e32 v175, 1.0, v175
	v_add_f32_e32 v176, 1.0, v176
	v_add_f32_e32 v177, 1.0, v177
	v_add_f32_e32 v178, 1.0, v178
	v_add_f32_e32 v179, 1.0, v179
	v_rcp_f32_e32 v172, v172
	v_rcp_f32_e32 v173, v173
	v_rcp_f32_e32 v174, v174
	v_rcp_f32_e32 v175, v175
	v_rcp_f32_e32 v176, v176
	v_rcp_f32_e32 v177, v177
	v_rcp_f32_e32 v178, v178
	v_rcp_f32_e32 v179, v179
	v_mul_f32_e32 v172, 0xbf60028b, v172
	v_mul_f32_e32 v173, 0xbf60028b, v173
	v_mul_f32_e32 v174, 0xbf60028b, v174
	v_mul_f32_e32 v175, 0xbf60028b, v175
	v_mul_f32_e32 v176, 0xbf60028b, v176
	v_mul_f32_e32 v177, 0xbf60028b, v177
	v_mul_f32_e32 v178, 0xbf60028b, v178
	v_mul_f32_e32 v179, 0xbf60028b, v179
	v_exp_f32_e32 v172, v172
	v_exp_f32_e32 v173, v173
	v_exp_f32_e32 v174, v174
	v_exp_f32_e32 v175, v175
	v_exp_f32_e32 v176, v176
	v_exp_f32_e32 v177, v177
	v_exp_f32_e32 v178, v178
	v_exp_f32_e32 v179, v179
	s_nop 0
	global_store_dwordx4 v[164:165], v[172:175], off
	global_store_dwordx4 v[164:165], v[176:179], off offset:16

;     __device__ __forceinline__ void operator()(f32x4 (&acc)[2][2][4][2], const Unit& u, int wr, int wc, int fr_, int fq_) const {
;     ...
;                     for (int m = 0; m < 4; ++m) { const size_t off = (size_t)(row0 + ai * HALF + m * 16) * 1024 + col0 + bj * HALF;
;                         f32x4 v0 = acc[ai][bj][m][0] + b0, v1 = acc[ai][bj][m][1] + b1;
;                         if (kind == 0) {
; #pragma unroll
;                             for (int i = 0; i < 4; ++i) { float z = -v0[i]; float sp = fmaxf(z, 0.f) + __logf(1.0f + __expf(-fabsf(z))); v0[i] = __expf(-__expf(-sp - 0.5f));
;                                                           z = -v1[i]; sp = fmaxf(z, 0.f) + __logf(1.0f + __expf(-fabsf(z))); v1[i] = __expf(-__expf(-sp - 0.5f)); }
;                             *(f32x4*)(DEC + off) = v0; *(f32x4*)(DEC + off + 4) = v1;
.LBB0_935:
	s_andn2_b64 vcc, exec, s[0:1]
	s_cbranch_vccnz .LBB0_937
	v_lshl_add_u64 v[166:167], v[166:167], 2, s[36:37]
	v_mul_f32_e32 v174, 0xbfb8aa3b, v174
	v_mul_f32_e32 v175, 0xbfb8aa3b, v175
	v_mul_f32_e32 v176, 0xbfb8aa3b, v170
	v_mul_f32_e32 v177, 0xbfb8aa3b, v171
	v_mul_f32_e32 v178, 0xbfb8aa3b, v172
	v_mul_f32_e32 v179, 0xbfb8aa3b, v173
	v_mul_f32_e32 v180, 0xbfb8aa3b, v168
	v_mul_f32_e32 v181, 0xbfb8aa3b, v169
	v_exp_f32_e32 v174, v174
	v_exp_f32_e32 v175, v175
	v_exp_f32_e32 v176, v176
	v_exp_f32_e32 v177, v177
	v_exp_f32_e32 v178, v178
	v_exp_f32_e32 v179, v179
	v_exp_f32_e32 v180, v180
	v_exp_f32_e32 v181, v181
	v_add_f32_e32 v174, 1.0, v174
	v_add_f32_e32 v175, 1.0, v175
	v_add_f32_e32 v176, 1.0, v176
	v_add_f32_e32 v177, 1.0, v177
	v_add_f32_e32 v178, 1.0, v178
	v_add_f32_e32 v179, 1.0, v179
	v_add_f32_e32 v180, 1.0, v180
	v_add_f32_e32 v181, 1.0, v181
	v_rcp_f32_e32 v174, v174
	v_rcp_f32_e32 v175, v175
	v_rcp_f32_e32 v176, v176
	v_rcp_f32_e32 v177, v177
	v_rcp_f32_e32 v178, v178
	v_rcp_f32_e32 v179, v179
	v_rcp_f32_e32 v180, v180
	v_rcp_f32_e32 v181, v181
	v_mul_f32_e32 v174, 0xbf60028b, v174
	v_mul_f32_e32 v175, 0xbf60028b, v175
	v_mul_f32_e32 v176, 0xbf60028b, v176
	v_mul_f32_e32 v177, 0xbf60028b, v177
	v_mul_f32_e32 v178, 0xbf60028b, v178
	v_mul_f32_e32 v179, 0xbf60028b, v179
	v_mul_f32_e32 v180, 0xbf60028b, v180
	v_mul_f32_e32 v181, 0xbf60028b, v181
	v_exp_f32_e32 v174, v174
	v_exp_f32_e32 v175, v175
	v_exp_f32_e32 v176, v176
	v_exp_f32_e32 v177, v177
	v_exp_f32_e32 v178, v178
	v_exp_f32_e32 v179, v179
	v_exp_f32_e32 v180, v180
	v_exp_f32_e32 v181, v181
	s_nop 0
	global_store_dwordx4 v[166:167], v[174:177], off
	global_store_dwordx4 v[166:167], v[178:181], off offset:16

;     __device__ __forceinline__ void operator()(f32x4 (&acc)[2][2][4][2], const Unit& u, int wr, int wc, int fr_, int fq_) const {
;     ...
;                     for (int m = 0; m < 4; ++m) { const size_t off = (size_t)(row0 + ai * HALF + m * 16) * 1024 + col0 + bj * HALF;
;                         f32x4 v0 = acc[ai][bj][m][0] + b0, v1 = acc[ai][bj][m][1] + b1;
;                         if (kind == 0) {
; #pragma unroll
;                             for (int i = 0; i < 4; ++i) { float z = -v0[i]; float sp = fmaxf(z, 0.f) + __logf(1.0f + __expf(-fabsf(z))); v0[i] = __expf(-__expf(-sp - 0.5f));
;                                                           z = -v1[i]; sp = fmaxf(z, 0.f) + __logf(1.0f + __expf(-fabsf(z))); v1[i] = __expf(-__expf(-sp - 0.5f)); }
;                             *(f32x4*)(DEC + off) = v0; *(f32x4*)(DEC + off + 4) = v1;
.LBB0_939:
	s_andn2_b64 vcc, exec, s[0:1]
	s_cbranch_vccnz .LBB0_941
	v_lshl_add_u64 v[168:169], v[168:169], 2, s[36:37]
	v_mul_f32_e32 v176, 0xbfb8aa3b, v176
	v_mul_f32_e32 v177, 0xbfb8aa3b, v177
	v_mul_f32_e32 v178, 0xbfb8aa3b, v172
	v_mul_f32_e32 v179, 0xbfb8aa3b, v173
	v_mul_f32_e32 v180, 0xbfb8aa3b, v174
	v_mul_f32_e32 v181, 0xbfb8aa3b, v175
	v_mul_f32_e32 v182, 0xbfb8aa3b, v170
	v_mul_f32_e32 v183, 0xbfb8aa3b, v171
	v_exp_f32_e32 v176, v176
	v_exp_f32_e32 v177, v177
	v_exp_f32_e32 v178, v178
	v_exp_f32_e32 v179, v179
	v_exp_f32_e32 v180, v180
	v_exp_f32_e32 v181, v181
	v_exp_f32_e32 v182, v182
	v_exp_f32_e32 v183, v183
	v_add_f32_e32 v176, 1.0, v176
	v_add_f32_e32 v177, 1.0, v177
	v_add_f32_e32 v178, 1.0, v178
	v_add_f32_e32 v179, 1.0, v179
	v_add_f32_e32 v180, 1.0, v180
	v_add_f32_e32 v181, 1.0, v181
	v_add_f32_e32 v182, 1.0, v182
	v_add_f32_e32 v183, 1.0, v183
	v_rcp_f32_e32 v176, v176
	v_rcp_f32_e32 v177, v177
	v_rcp_f32_e32 v178, v178
	v_rcp_f32_e32 v179, v179
	v_rcp_f32_e32 v180, v180
	v_rcp_f32_e32 v181, v181
	v_rcp_f32_e32 v182, v182
	v_rcp_f32_e32 v183, v183
	v_mul_f32_e32 v176, 0xbf60028b, v176
	v_mul_f32_e32 v177, 0xbf60028b, v177
	v_mul_f32_e32 v178, 0xbf60028b, v178
	v_mul_f32_e32 v179, 0xbf60028b, v179
	v_mul_f32_e32 v180, 0xbf60028b, v180
	v_mul_f32_e32 v181, 0xbf60028b, v181
	v_mul_f32_e32 v182, 0xbf60028b, v182
	v_mul_f32_e32 v183, 0xbf60028b, v183
	v_exp_f32_e32 v176, v176
	v_exp_f32_e32 v177, v177
	v_exp_f32_e32 v178, v178
	v_exp_f32_e32 v179, v179
	v_exp_f32_e32 v180, v180
	v_exp_f32_e32 v181, v181
	v_exp_f32_e32 v182, v182
	v_exp_f32_e32 v183, v183
	s_nop 0
	global_store_dwordx4 v[168:169], v[176:179], off
	global_store_dwordx4 v[168:169], v[180:183], off offset:16

;     __device__ __forceinline__ void operator()(f32x4 (&acc)[2][2][4][2], const Unit& u, int wr, int wc, int fr_, int fq_) const {
;     ...
;                     for (int m = 0; m < 4; ++m) { const size_t off = (size_t)(row0 + ai * HALF + m * 16) * 1024 + col0 + bj * HALF;
;                         f32x4 v0 = acc[ai][bj][m][0] + b0, v1 = acc[ai][bj][m][1] + b1;
;                         if (kind == 0) {
; #pragma unroll
;                             for (int i = 0; i < 4; ++i) { float z = -v0[i]; float sp = fmaxf(z, 0.f) + __logf(1.0f + __expf(-fabsf(z))); v0[i] = __expf(-__expf(-sp - 0.5f));
;                                                           z = -v1[i]; sp = fmaxf(z, 0.f) + __logf(1.0f + __expf(-fabsf(z))); v1[i] = __expf(-__expf(-sp - 0.5f)); }
;                             *(f32x4*)(DEC + off) = v0; *(f32x4*)(DEC + off + 4) = v1;
.LBB0_943:
	s_andn2_b64 vcc, exec, s[0:1]
	s_cbranch_vccnz .LBB0_945
	v_lshl_add_u64 v[170:171], v[170:171], 2, s[36:37]
	v_mul_f32_e32 v178, 0xbfb8aa3b, v178
	v_mul_f32_e32 v179, 0xbfb8aa3b, v179
	v_mul_f32_e32 v180, 0xbfb8aa3b, v174
	v_mul_f32_e32 v181, 0xbfb8aa3b, v175
	v_mul_f32_e32 v192, 0xbfb8aa3b, v176
	v_mul_f32_e32 v193, 0xbfb8aa3b, v177
	v_mul_f32_e32 v194, 0xbfb8aa3b, v172
	v_mul_f32_e32 v195, 0xbfb8aa3b, v173
	v_exp_f32_e32 v178, v178
	v_exp_f32_e32 v179, v179
	v_exp_f32_e32 v180, v180
	v_exp_f32_e32 v181, v181
	v_exp_f32_e32 v192, v192
	v_exp_f32_e32 v193, v193
	v_exp_f32_e32 v194, v194
	v_exp_f32_e32 v195, v195
	v_add_f32_e32 v178, 1.0, v178
	v_add_f32_e32 v179, 1.0, v179
	v_add_f32_e32 v180, 1.0, v180
	v_add_f32_e32 v181, 1.0, v181
	v_add_f32_e32 v192, 1.0, v192
	v_add_f32_e32 v193, 1.0, v193
	v_add_f32_e32 v194, 1.0, v194
	v_add_f32_e32 v195, 1.0, v195
	v_rcp_f32_e32 v178, v178
	v_rcp_f32_e32 v179, v179
	v_rcp_f32_e32 v180, v180
	v_rcp_f32_e32 v181, v181
	v_rcp_f32_e32 v192, v192
	v_rcp_f32_e32 v193, v193
	v_rcp_f32_e32 v194, v194
	v_rcp_f32_e32 v195, v195
	v_mul_f32_e32 v178, 0xbf60028b, v178
	v_mul_f32_e32 v179, 0xbf60028b, v179
	v_mul_f32_e32 v180, 0xbf60028b, v180
	v_mul_f32_e32 v181, 0xbf60028b, v181
	v_mul_f32_e32 v192, 0xbf60028b, v192
	v_mul_f32_e32 v193, 0xbf60028b, v193
	v_mul_f32_e32 v194, 0xbf60028b, v194
	v_mul_f32_e32 v195, 0xbf60028b, v195
	v_exp_f32_e32 v178, v178
	v_exp_f32_e32 v179, v179
	v_exp_f32_e32 v180, v180
	v_exp_f32_e32 v181, v181
	v_exp_f32_e32 v192, v192
	v_exp_f32_e32 v193, v193
	v_exp_f32_e32 v194, v194
	v_exp_f32_e32 v195, v195
	s_nop 0
	global_store_dwordx4 v[170:171], v[178:181], off
	global_store_dwordx4 v[170:171], v[192:195], off offset:16

;     __device__ __forceinline__ void operator()(f32x4 (&acc)[2][2][4][2], const Unit& u, int wr, int wc, int fr_, int fq_) const {
;     ...
;                     for (int m = 0; m < 4; ++m) { const size_t off = (size_t)(row0 + ai * HALF + m * 16) * 1024 + col0 + bj * HALF;
;                         f32x4 v0 = acc[ai][bj][m][0] + b0, v1 = acc[ai][bj][m][1] + b1;
;                         if (kind == 0) {
; #pragma unroll
;                             for (int i = 0; i < 4; ++i) { float z = -v0[i]; float sp = fmaxf(z, 0.f) + __logf(1.0f + __expf(-fabsf(z))); v0[i] = __expf(-__expf(-sp - 0.5f));
;                                                           z = -v1[i]; sp = fmaxf(z, 0.f) + __logf(1.0f + __expf(-fabsf(z))); v1[i] = __expf(-__expf(-sp - 0.5f)); }
;                             *(f32x4*)(DEC + off) = v0; *(f32x4*)(DEC + off + 4) = v1;
.LBB0_947:
	s_andn2_b64 vcc, exec, s[0:1]
	s_cbranch_vccnz .LBB0_949
	v_lshl_add_u64 v[172:173], v[172:173], 2, s[36:37]
	v_mul_f32_e32 v180, 0xbfb8aa3b, v180
	v_mul_f32_e32 v181, 0xbfb8aa3b, v181
	v_mul_f32_e32 v182, 0xbfb8aa3b, v176
	v_mul_f32_e32 v183, 0xbfb8aa3b, v177
	v_mul_f32_e32 v192, 0xbfb8aa3b, v178
	v_mul_f32_e32 v193, 0xbfb8aa3b, v179
	v_mul_f32_e32 v194, 0xbfb8aa3b, v174
	v_mul_f32_e32 v195, 0xbfb8aa3b, v175
	v_exp_f32_e32 v180, v180
	v_exp_f32_e32 v181, v181
	v_exp_f32_e32 v182, v182
	v_exp_f32_e32 v183, v183
	v_exp_f32_e32 v192, v192
	v_exp_f32_e32 v193, v193
	v_exp_f32_e32 v194, v194
	v_exp_f32_e32 v195, v195
	v_add_f32_e32 v180, 1.0, v180
	v_add_f32_e32 v181, 1.0, v181
	v_add_f32_e32 v182, 1.0, v182
	v_add_f32_e32 v183, 1.0, v183
	v_add_f32_e32 v192, 1.0, v192
	v_add_f32_e32 v193, 1.0, v193
	v_add_f32_e32 v194, 1.0, v194
	v_add_f32_e32 v195, 1.0, v195
	v_rcp_f32_e32 v180, v180
	v_rcp_f32_e32 v181, v181
	v_rcp_f32_e32 v182, v182
	v_rcp_f32_e32 v183, v183
	v_rcp_f32_e32 v192, v192
	v_rcp_f32_e32 v193, v193
	v_rcp_f32_e32 v194, v194
	v_rcp_f32_e32 v195, v195
	v_mul_f32_e32 v180, 0xbf60028b, v180
	v_mul_f32_e32 v181, 0xbf60028b, v181
	v_mul_f32_e32 v182, 0xbf60028b, v182
	v_mul_f32_e32 v183, 0xbf60028b, v183
	v_mul_f32_e32 v192, 0xbf60028b, v192
	v_mul_f32_e32 v193, 0xbf60028b, v193
	v_mul_f32_e32 v194, 0xbf60028b, v194
	v_mul_f32_e32 v195, 0xbf60028b, v195
	v_exp_f32_e32 v180, v180
	v_exp_f32_e32 v181, v181
	v_exp_f32_e32 v182, v182
	v_exp_f32_e32 v183, v183
	v_exp_f32_e32 v192, v192
	v_exp_f32_e32 v193, v193
	v_exp_f32_e32 v194, v194
	v_exp_f32_e32 v195, v195
	s_nop 0
	global_store_dwordx4 v[172:173], v[180:183], off
	global_store_dwordx4 v[172:173], v[192:195], off offset:16

;     __device__ __forceinline__ void operator()(f32x4 (&acc)[2][2][4][2], const Unit& u, int wr, int wc, int fr_, int fq_) const {
;     ...
;                     for (int m = 0; m < 4; ++m) { const size_t off = (size_t)(row0 + ai * HALF + m * 16) * 1024 + col0 + bj * HALF;
;                         f32x4 v0 = acc[ai][bj][m][0] + b0, v1 = acc[ai][bj][m][1] + b1;
;                         if (kind == 0) {
; #pragma unroll
;                             for (int i = 0; i < 4; ++i) { float z = -v0[i]; float sp = fmaxf(z, 0.f) + __logf(1.0f + __expf(-fabsf(z))); v0[i] = __expf(-__expf(-sp - 0.5f));
;                                                           z = -v1[i]; sp = fmaxf(z, 0.f) + __logf(1.0f + __expf(-fabsf(z))); v1[i] = __expf(-__expf(-sp - 0.5f)); }
;                             *(f32x4*)(DEC + off) = v0; *(f32x4*)(DEC + off + 4) = v1;
.LBB0_951:
	s_andn2_b64 vcc, exec, s[0:1]
	s_cbranch_vccnz .LBB0_953
	v_lshl_add_u64 v[174:175], v[174:175], 2, s[36:37]
	v_mul_f32_e32 v192, 0xbfb8aa3b, v182
	v_mul_f32_e32 v193, 0xbfb8aa3b, v183
	v_mul_f32_e32 v194, 0xbfb8aa3b, v178
	v_mul_f32_e32 v195, 0xbfb8aa3b, v179
	v_mul_f32_e32 v180, 0xbfb8aa3b, v180
	v_mul_f32_e32 v181, 0xbfb8aa3b, v181
	v_mul_f32_e32 v182, 0xbfb8aa3b, v176
	v_mul_f32_e32 v183, 0xbfb8aa3b, v177
	v_exp_f32_e32 v192, v192
	v_exp_f32_e32 v193, v193
	v_exp_f32_e32 v194, v194
	v_exp_f32_e32 v195, v195
	v_exp_f32_e32 v180, v180
	v_exp_f32_e32 v181, v181
	v_exp_f32_e32 v182, v182
	v_exp_f32_e32 v183, v183
	v_add_f32_e32 v192, 1.0, v192
	v_add_f32_e32 v193, 1.0, v193
	v_add_f32_e32 v194, 1.0, v194
	v_add_f32_e32 v195, 1.0, v195
	v_add_f32_e32 v180, 1.0, v180
	v_add_f32_e32 v181, 1.0, v181
	v_add_f32_e32 v182, 1.0, v182
	v_add_f32_e32 v183, 1.0, v183
	v_rcp_f32_e32 v192, v192
	v_rcp_f32_e32 v193, v193
	v_rcp_f32_e32 v194, v194
	v_rcp_f32_e32 v195, v195
	v_rcp_f32_e32 v180, v180
	v_rcp_f32_e32 v181, v181
	v_rcp_f32_e32 v182, v182
	v_rcp_f32_e32 v183, v183
	v_mul_f32_e32 v192, 0xbf60028b, v192
	v_mul_f32_e32 v193, 0xbf60028b, v193
	v_mul_f32_e32 v194, 0xbf60028b, v194
	v_mul_f32_e32 v195, 0xbf60028b, v195
	v_mul_f32_e32 v180, 0xbf60028b, v180
	v_mul_f32_e32 v181, 0xbf60028b, v181
	v_mul_f32_e32 v182, 0xbf60028b, v182
	v_mul_f32_e32 v183, 0xbf60028b, v183
	v_exp_f32_e32 v192, v192
	v_exp_f32_e32 v193, v193
	v_exp_f32_e32 v194, v194
	v_exp_f32_e32 v195, v195
	v_exp_f32_e32 v180, v180
	v_exp_f32_e32 v181, v181
	v_exp_f32_e32 v182, v182
	v_exp_f32_e32 v183, v183
	s_nop 0
	global_store_dwordx4 v[174:175], v[192:195], off
	global_store_dwordx4 v[174:175], v[180:183], off offset:16

;     __device__ __forceinline__ void operator()(f32x4 (&acc)[2][2][4][2], const Unit& u, int wr, int wc, int fr_, int fq_) const {
;     ...
;                     for (int m = 0; m < 4; ++m) { const size_t off = (size_t)(row0 + ai * HALF + m * 16) * 1024 + col0 + bj * HALF;
;                         f32x4 v0 = acc[ai][bj][m][0] + b0, v1 = acc[ai][bj][m][1] + b1;
;                         if (kind == 0) {
; #pragma unroll
;                             for (int i = 0; i < 4; ++i) { float z = -v0[i]; float sp = fmaxf(z, 0.f) + __logf(1.0f + __expf(-fabsf(z))); v0[i] = __expf(-__expf(-sp - 0.5f));
;                                                           z = -v1[i]; sp = fmaxf(z, 0.f) + __logf(1.0f + __expf(-fabsf(z))); v1[i] = __expf(-__expf(-sp - 0.5f)); }
;                             *(f32x4*)(DEC + off) = v0; *(f32x4*)(DEC + off + 4) = v1;
.LBB0_955:
	s_andn2_b64 vcc, exec, s[0:1]
	s_cbranch_vccnz .LBB0_957
	v_lshl_add_u64 v[176:177], v[176:177], 2, s[36:37]
	v_mul_f32_e32 v132, 0xbfb8aa3b, v132
	v_mul_f32_e32 v133, 0xbfb8aa3b, v133
	v_mul_f32_e32 v134, 0xbfb8aa3b, v134
	v_mul_f32_e32 v135, 0xbfb8aa3b, v135
	v_mul_f32_e32 v128, 0xbfb8aa3b, v128
	v_mul_f32_e32 v129, 0xbfb8aa3b, v129
	v_mul_f32_e32 v130, 0xbfb8aa3b, v130
	v_mul_f32_e32 v131, 0xbfb8aa3b, v131
	v_exp_f32_e32 v132, v132
	v_exp_f32_e32 v133, v133
	v_exp_f32_e32 v134, v134
	v_exp_f32_e32 v135, v135
	v_exp_f32_e32 v128, v128
	v_exp_f32_e32 v129, v129
	v_exp_f32_e32 v130, v130
	v_exp_f32_e32 v131, v131
	v_add_f32_e32 v132, 1.0, v132
	v_add_f32_e32 v133, 1.0, v133
	v_add_f32_e32 v134, 1.0, v134
	v_add_f32_e32 v135, 1.0, v135
	v_add_f32_e32 v128, 1.0, v128
	v_add_f32_e32 v129, 1.0, v129
	v_add_f32_e32 v130, 1.0, v130
	v_add_f32_e32 v131, 1.0, v131
	v_rcp_f32_e32 v132, v132
	v_rcp_f32_e32 v133, v133
	v_rcp_f32_e32 v134, v134
	v_rcp_f32_e32 v135, v135
	v_rcp_f32_e32 v128, v128
	v_rcp_f32_e32 v129, v129
	v_rcp_f32_e32 v130, v130
	v_rcp_f32_e32 v131, v131
	v_mul_f32_e32 v132, 0xbf60028b, v132
	v_mul_f32_e32 v133, 0xbf60028b, v133
	v_mul_f32_e32 v134, 0xbf60028b, v134
	v_mul_f32_e32 v135, 0xbf60028b, v135
	v_mul_f32_e32 v128, 0xbf60028b, v128
	v_mul_f32_e32 v129, 0xbf60028b, v129
	v_mul_f32_e32 v130, 0xbf60028b, v130
	v_mul_f32_e32 v131, 0xbf60028b, v131
	v_exp_f32_e32 v132, v132
	v_exp_f32_e32 v133, v133
	v_exp_f32_e32 v134, v134
	v_exp_f32_e32 v135, v135
	v_exp_f32_e32 v128, v128
	v_exp_f32_e32 v129, v129
	v_exp_f32_e32 v130, v130
	v_exp_f32_e32 v131, v131
	s_nop 0
	global_store_dwordx4 v[176:177], v[132:135], off
	global_store_dwordx4 v[176:177], v[128:131], off offset:16

;     __device__ __forceinline__ void operator()(f32x4 (&acc)[2][2][4][2], const Unit& u, int wr, int wc, int fr_, int fq_) const {
;     ...
;                     for (int m = 0; m < 4; ++m) { const size_t off = (size_t)(row0 + ai * HALF + m * 16) * 1024 + col0 + bj * HALF;
;                         f32x4 v0 = acc[ai][bj][m][0] + b0, v1 = acc[ai][bj][m][1] + b1;
;                         if (kind == 0) {
; #pragma unroll
;                             for (int i = 0; i < 4; ++i) { float z = -v0[i]; float sp = fmaxf(z, 0.f) + __logf(1.0f + __expf(-fabsf(z))); v0[i] = __expf(-__expf(-sp - 0.5f));
;                                                           z = -v1[i]; sp = fmaxf(z, 0.f) + __logf(1.0f + __expf(-fabsf(z))); v1[i] = __expf(-__expf(-sp - 0.5f)); }
;                             *(f32x4*)(DEC + off) = v0; *(f32x4*)(DEC + off + 4) = v1;
.LBB0_959:
	s_andn2_b64 vcc, exec, s[0:1]
	s_cbranch_vccnz .LBB0_961
	v_lshl_add_u64 v[158:159], v[158:159], 2, s[36:37]
	v_mul_f32_e32 v192, 0xbfb8aa3b, v182
	v_mul_f32_e32 v193, 0xbfb8aa3b, v183
	v_mul_f32_e32 v194, 0xbfb8aa3b, v178
	v_mul_f32_e32 v195, 0xbfb8aa3b, v179
	v_mul_f32_e32 v180, 0xbfb8aa3b, v180
	v_mul_f32_e32 v181, 0xbfb8aa3b, v181
	v_mul_f32_e32 v182, 0xbfb8aa3b, v176
	v_mul_f32_e32 v183, 0xbfb8aa3b, v177
	v_exp_f32_e32 v192, v192
	v_exp_f32_e32 v193, v193
	v_exp_f32_e32 v194, v194
	v_exp_f32_e32 v195, v195
	v_exp_f32_e32 v180, v180
	v_exp_f32_e32 v181, v181
	v_exp_f32_e32 v182, v182
	v_exp_f32_e32 v183, v183
	v_add_f32_e32 v192, 1.0, v192
	v_add_f32_e32 v193, 1.0, v193
	v_add_f32_e32 v194, 1.0, v194
	v_add_f32_e32 v195, 1.0, v195
	v_add_f32_e32 v180, 1.0, v180
	v_add_f32_e32 v181, 1.0, v181
	v_add_f32_e32 v182, 1.0, v182
	v_add_f32_e32 v183, 1.0, v183
	v_rcp_f32_e32 v192, v192
	v_rcp_f32_e32 v193, v193
	v_rcp_f32_e32 v194, v194
	v_rcp_f32_e32 v195, v195
	v_rcp_f32_e32 v180, v180
	v_rcp_f32_e32 v181, v181
	v_rcp_f32_e32 v182, v182
	v_rcp_f32_e32 v183, v183
	v_mul_f32_e32 v192, 0xbf60028b, v192
	v_mul_f32_e32 v193, 0xbf60028b, v193
	v_mul_f32_e32 v194, 0xbf60028b, v194
	v_mul_f32_e32 v195, 0xbf60028b, v195
	v_mul_f32_e32 v180, 0xbf60028b, v180
	v_mul_f32_e32 v181, 0xbf60028b, v181
	v_mul_f32_e32 v182, 0xbf60028b, v182
	v_mul_f32_e32 v183, 0xbf60028b, v183
	v_exp_f32_e32 v192, v192
	v_exp_f32_e32 v193, v193
	v_exp_f32_e32 v194, v194
	v_exp_f32_e32 v195, v195
	v_exp_f32_e32 v180, v180
	v_exp_f32_e32 v181, v181
	v_exp_f32_e32 v182, v182
	v_exp_f32_e32 v183, v183
	s_nop 0
	global_store_dwordx4 v[158:159], v[192:195], off
	global_store_dwordx4 v[158:159], v[180:183], off offset:16

;     __device__ __forceinline__ void operator()(f32x4 (&acc)[2][2][4][2], const Unit& u, int wr, int wc, int fr_, int fq_) const {
;     ...
;                     for (int m = 0; m < 4; ++m) { const size_t off = (size_t)(row0 + ai * HALF + m * 16) * 1024 + col0 + bj * HALF;
;                         f32x4 v0 = acc[ai][bj][m][0] + b0, v1 = acc[ai][bj][m][1] + b1;
;                         if (kind == 0) {
; #pragma unroll
;                             for (int i = 0; i < 4; ++i) { float z = -v0[i]; float sp = fmaxf(z, 0.f) + __logf(1.0f + __expf(-fabsf(z))); v0[i] = __expf(-__expf(-sp - 0.5f));
;                                                           z = -v1[i]; sp = fmaxf(z, 0.f) + __logf(1.0f + __expf(-fabsf(z))); v1[i] = __expf(-__expf(-sp - 0.5f)); }
;                             *(f32x4*)(DEC + off) = v0; *(f32x4*)(DEC + off + 4) = v1;
.LBB0_963:
	s_andn2_b64 vcc, exec, s[0:1]
	s_cbranch_vccnz .LBB0_965
	v_lshl_add_u64 v[158:159], v[158:159], 2, s[36:37]
	v_mul_f32_e32 v180, 0xbfb8aa3b, v180
	v_mul_f32_e32 v181, 0xbfb8aa3b, v181
	v_mul_f32_e32 v182, 0xbfb8aa3b, v176
	v_mul_f32_e32 v183, 0xbfb8aa3b, v177
	v_mul_f32_e32 v192, 0xbfb8aa3b, v178
	v_mul_f32_e32 v193, 0xbfb8aa3b, v179
	v_mul_f32_e32 v194, 0xbfb8aa3b, v162
	v_mul_f32_e32 v195, 0xbfb8aa3b, v163
	v_exp_f32_e32 v180, v180
	v_exp_f32_e32 v181, v181
	v_exp_f32_e32 v182, v182
	v_exp_f32_e32 v183, v183
	v_exp_f32_e32 v192, v192
	v_exp_f32_e32 v193, v193
	v_exp_f32_e32 v194, v194
	v_exp_f32_e32 v195, v195
	v_add_f32_e32 v180, 1.0, v180
	v_add_f32_e32 v181, 1.0, v181
	v_add_f32_e32 v182, 1.0, v182
	v_add_f32_e32 v183, 1.0, v183
	v_add_f32_e32 v192, 1.0, v192
	v_add_f32_e32 v193, 1.0, v193
	v_add_f32_e32 v194, 1.0, v194
	v_add_f32_e32 v195, 1.0, v195
	v_rcp_f32_e32 v180, v180
	v_rcp_f32_e32 v181, v181
	v_rcp_f32_e32 v182, v182
	v_rcp_f32_e32 v183, v183
	v_rcp_f32_e32 v192, v192
	v_rcp_f32_e32 v193, v193
	v_rcp_f32_e32 v194, v194
	v_rcp_f32_e32 v195, v195
	v_mul_f32_e32 v180, 0xbf60028b, v180
	v_mul_f32_e32 v181, 0xbf60028b, v181
	v_mul_f32_e32 v182, 0xbf60028b, v182
	v_mul_f32_e32 v183, 0xbf60028b, v183
	v_mul_f32_e32 v192, 0xbf60028b, v192
	v_mul_f32_e32 v193, 0xbf60028b, v193
	v_mul_f32_e32 v194, 0xbf60028b, v194
	v_mul_f32_e32 v195, 0xbf60028b, v195
	v_exp_f32_e32 v180, v180
	v_exp_f32_e32 v181, v181
	v_exp_f32_e32 v182, v182
	v_exp_f32_e32 v183, v183
	v_exp_f32_e32 v192, v192
	v_exp_f32_e32 v193, v193
	v_exp_f32_e32 v194, v194
	v_exp_f32_e32 v195, v195
	s_nop 0
	global_store_dwordx4 v[158:159], v[180:183], off
	global_store_dwordx4 v[158:159], v[192:195], off offset:16

;     __device__ __forceinline__ void operator()(f32x4 (&acc)[2][2][4][2], const Unit& u, int wr, int wc, int fr_, int fq_) const {
;     ...
;                     for (int m = 0; m < 4; ++m) { const size_t off = (size_t)(row0 + ai * HALF + m * 16) * 1024 + col0 + bj * HALF;
;                         f32x4 v0 = acc[ai][bj][m][0] + b0, v1 = acc[ai][bj][m][1] + b1;
;                         if (kind == 0) {
; #pragma unroll
;                             for (int i = 0; i < 4; ++i) { float z = -v0[i]; float sp = fmaxf(z, 0.f) + __logf(1.0f + __expf(-fabsf(z))); v0[i] = __expf(-__expf(-sp - 0.5f));
;                                                           z = -v1[i]; sp = fmaxf(z, 0.f) + __logf(1.0f + __expf(-fabsf(z))); v1[i] = __expf(-__expf(-sp - 0.5f)); }
;                             *(f32x4*)(DEC + off) = v0; *(f32x4*)(DEC + off + 4) = v1;
.LBB0_967:
	s_andn2_b64 vcc, exec, s[0:1]
	s_cbranch_vccnz .LBB0_969
	v_lshl_add_u64 v[158:159], v[158:159], 2, s[36:37]
	v_mul_f32_e32 v178, 0xbfb8aa3b, v178
	v_mul_f32_e32 v179, 0xbfb8aa3b, v179
	v_mul_f32_e32 v180, 0xbfb8aa3b, v164
	v_mul_f32_e32 v181, 0xbfb8aa3b, v165
	v_mul_f32_e32 v192, 0xbfb8aa3b, v176
	v_mul_f32_e32 v193, 0xbfb8aa3b, v177
	v_mul_f32_e32 v194, 0xbfb8aa3b, v162
	v_mul_f32_e32 v195, 0xbfb8aa3b, v163
	v_exp_f32_e32 v178, v178
	v_exp_f32_e32 v179, v179
	v_exp_f32_e32 v180, v180
	v_exp_f32_e32 v181, v181
	v_exp_f32_e32 v192, v192
	v_exp_f32_e32 v193, v193
	v_exp_f32_e32 v194, v194
	v_exp_f32_e32 v195, v195
	v_add_f32_e32 v178, 1.0, v178
	v_add_f32_e32 v179, 1.0, v179
	v_add_f32_e32 v180, 1.0, v180
	v_add_f32_e32 v181, 1.0, v181
	v_add_f32_e32 v192, 1.0, v192
	v_add_f32_e32 v193, 1.0, v193
	v_add_f32_e32 v194, 1.0, v194
	v_add_f32_e32 v195, 1.0, v195
	v_rcp_f32_e32 v178, v178
	v_rcp_f32_e32 v179, v179
	v_rcp_f32_e32 v180, v180
	v_rcp_f32_e32 v181, v181
	v_rcp_f32_e32 v192, v192
	v_rcp_f32_e32 v193, v193
	v_rcp_f32_e32 v194, v194
	v_rcp_f32_e32 v195, v195
	v_mul_f32_e32 v178, 0xbf60028b, v178
	v_mul_f32_e32 v179, 0xbf60028b, v179
	v_mul_f32_e32 v180, 0xbf60028b, v180
	v_mul_f32_e32 v181, 0xbf60028b, v181
	v_mul_f32_e32 v192, 0xbf60028b, v192
	v_mul_f32_e32 v193, 0xbf60028b, v193
	v_mul_f32_e32 v194, 0xbf60028b, v194
	v_mul_f32_e32 v195, 0xbf60028b, v195
	v_exp_f32_e32 v178, v178
	v_exp_f32_e32 v179, v179
	v_exp_f32_e32 v180, v180
	v_exp_f32_e32 v181, v181
	v_exp_f32_e32 v192, v192
	v_exp_f32_e32 v193, v193
	v_exp_f32_e32 v194, v194
	v_exp_f32_e32 v195, v195
	s_nop 0
	global_store_dwordx4 v[158:159], v[178:181], off
	global_store_dwordx4 v[158:159], v[192:195], off offset:16

;     __device__ __forceinline__ void operator()(f32x4 (&acc)[2][2][4][2], const Unit& u, int wr, int wc, int fr_, int fq_) const {
;     ...
;                     for (int m = 0; m < 4; ++m) { const size_t off = (size_t)(row0 + ai * HALF + m * 16) * 1024 + col0 + bj * HALF;
;                         f32x4 v0 = acc[ai][bj][m][0] + b0, v1 = acc[ai][bj][m][1] + b1;
;                         if (kind == 0) {
; #pragma unroll
;                             for (int i = 0; i < 4; ++i) { float z = -v0[i]; float sp = fmaxf(z, 0.f) + __logf(1.0f + __expf(-fabsf(z))); v0[i] = __expf(-__expf(-sp - 0.5f));
;                                                           z = -v1[i]; sp = fmaxf(z, 0.f) + __logf(1.0f + __expf(-fabsf(z))); v1[i] = __expf(-__expf(-sp - 0.5f)); }
;                             *(f32x4*)(DEC + off) = v0; *(f32x4*)(DEC + off + 4) = v1;
.LBB0_971:
	s_andn2_b64 vcc, exec, s[0:1]
	s_cbranch_vccnz .LBB0_973
	v_lshl_add_u64 v[158:159], v[158:159], 2, s[36:37]
	v_mul_f32_e32 v176, 0xbfb8aa3b, v176
	v_mul_f32_e32 v177, 0xbfb8aa3b, v177
	v_mul_f32_e32 v178, 0xbfb8aa3b, v164
	v_mul_f32_e32 v179, 0xbfb8aa3b, v165
	v_mul_f32_e32 v180, 0xbfb8aa3b, v166
	v_mul_f32_e32 v181, 0xbfb8aa3b, v167
	v_mul_f32_e32 v182, 0xbfb8aa3b, v162
	v_mul_f32_e32 v183, 0xbfb8aa3b, v163
	v_exp_f32_e32 v176, v176
	v_exp_f32_e32 v177, v177
	v_exp_f32_e32 v178, v178
	v_exp_f32_e32 v179, v179
	v_exp_f32_e32 v180, v180
	v_exp_f32_e32 v181, v181
	v_exp_f32_e32 v182, v182
	v_exp_f32_e32 v183, v183
	v_add_f32_e32 v176, 1.0, v176
	v_add_f32_e32 v177, 1.0, v177
	v_add_f32_e32 v178, 1.0, v178
	v_add_f32_e32 v179, 1.0, v179
	v_add_f32_e32 v180, 1.0, v180
	v_add_f32_e32 v181, 1.0, v181
	v_add_f32_e32 v182, 1.0, v182
	v_add_f32_e32 v183, 1.0, v183
	v_rcp_f32_e32 v176, v176
	v_rcp_f32_e32 v177, v177
	v_rcp_f32_e32 v178, v178
	v_rcp_f32_e32 v179, v179
	v_rcp_f32_e32 v180, v180
	v_rcp_f32_e32 v181, v181
	v_rcp_f32_e32 v182, v182
	v_rcp_f32_e32 v183, v183
	v_mul_f32_e32 v176, 0xbf60028b, v176
	v_mul_f32_e32 v177, 0xbf60028b, v177
	v_mul_f32_e32 v178, 0xbf60028b, v178
	v_mul_f32_e32 v179, 0xbf60028b, v179
	v_mul_f32_e32 v180, 0xbf60028b, v180
	v_mul_f32_e32 v181, 0xbf60028b, v181
	v_mul_f32_e32 v182, 0xbf60028b, v182
	v_mul_f32_e32 v183, 0xbf60028b, v183
	v_exp_f32_e32 v176, v176
	v_exp_f32_e32 v177, v177
	v_exp_f32_e32 v178, v178
	v_exp_f32_e32 v179, v179
	v_exp_f32_e32 v180, v180
	v_exp_f32_e32 v181, v181
	v_exp_f32_e32 v182, v182
	v_exp_f32_e32 v183, v183
	s_nop 0
	global_store_dwordx4 v[158:159], v[176:179], off
	global_store_dwordx4 v[158:159], v[180:183], off offset:16

;     __device__ __forceinline__ void operator()(f32x4 (&acc)[2][2][4][2], const Unit& u, int wr, int wc, int fr_, int fq_) const {
;     ...
;                     for (int m = 0; m < 4; ++m) { const size_t off = (size_t)(row0 + ai * HALF + m * 16) * 1024 + col0 + bj * HALF;
;                         f32x4 v0 = acc[ai][bj][m][0] + b0, v1 = acc[ai][bj][m][1] + b1;
;                         if (kind == 0) {
; #pragma unroll
;                             for (int i = 0; i < 4; ++i) { float z = -v0[i]; float sp = fmaxf(z, 0.f) + __logf(1.0f + __expf(-fabsf(z))); v0[i] = __expf(-__expf(-sp - 0.5f));
;                                                           z = -v1[i]; sp = fmaxf(z, 0.f) + __logf(1.0f + __expf(-fabsf(z))); v1[i] = __expf(-__expf(-sp - 0.5f)); }
;                             *(f32x4*)(DEC + off) = v0; *(f32x4*)(DEC + off + 4) = v1;
.LBB0_975:
	s_andn2_b64 vcc, exec, s[0:1]
	s_cbranch_vccnz .LBB0_977
	v_lshl_add_u64 v[158:159], v[158:159], 2, s[36:37]
	v_mul_f32_e32 v176, 0xbfb8aa3b, v168
	v_mul_f32_e32 v177, 0xbfb8aa3b, v169
	v_mul_f32_e32 v178, 0xbfb8aa3b, v164
	v_mul_f32_e32 v179, 0xbfb8aa3b, v165
	v_mul_f32_e32 v166, 0xbfb8aa3b, v166
	v_mul_f32_e32 v167, 0xbfb8aa3b, v167
	v_mul_f32_e32 v168, 0xbfb8aa3b, v162
	v_mul_f32_e32 v169, 0xbfb8aa3b, v163
	v_exp_f32_e32 v176, v176
	v_exp_f32_e32 v177, v177
	v_exp_f32_e32 v178, v178
	v_exp_f32_e32 v179, v179
	v_exp_f32_e32 v166, v166
	v_exp_f32_e32 v167, v167
	v_exp_f32_e32 v168, v168
	v_exp_f32_e32 v169, v169
	v_add_f32_e32 v176, 1.0, v176
	v_add_f32_e32 v177, 1.0, v177
	v_add_f32_e32 v178, 1.0, v178
	v_add_f32_e32 v179, 1.0, v179
	v_add_f32_e32 v166, 1.0, v166
	v_add_f32_e32 v167, 1.0, v167
	v_add_f32_e32 v168, 1.0, v168
	v_add_f32_e32 v169, 1.0, v169
	v_rcp_f32_e32 v176, v176
	v_rcp_f32_e32 v177, v177
	v_rcp_f32_e32 v178, v178
	v_rcp_f32_e32 v179, v179
	v_rcp_f32_e32 v166, v166
	v_rcp_f32_e32 v167, v167
	v_rcp_f32_e32 v168, v168
	v_rcp_f32_e32 v169, v169
	v_mul_f32_e32 v176, 0xbf60028b, v176
	v_mul_f32_e32 v177, 0xbf60028b, v177
	v_mul_f32_e32 v178, 0xbf60028b, v178
	v_mul_f32_e32 v179, 0xbf60028b, v179
	v_mul_f32_e32 v166, 0xbf60028b, v166
	v_mul_f32_e32 v167, 0xbf60028b, v167
	v_mul_f32_e32 v168, 0xbf60028b, v168
	v_mul_f32_e32 v169, 0xbf60028b, v169
	v_exp_f32_e32 v176, v176
	v_exp_f32_e32 v177, v177
	v_exp_f32_e32 v178, v178
	v_exp_f32_e32 v179, v179
	v_exp_f32_e32 v166, v166
	v_exp_f32_e32 v167, v167
	v_exp_f32_e32 v168, v168
	v_exp_f32_e32 v169, v169
	s_nop 0
	global_store_dwordx4 v[158:159], v[176:179], off
	global_store_dwordx4 v[158:159], v[166:169], off offset:16

;     __device__ __forceinline__ void operator()(f32x4 (&acc)[2][2][4][2], const Unit& u, int wr, int wc, int fr_, int fq_) const {
;     ...
;                     for (int m = 0; m < 4; ++m) { const size_t off = (size_t)(row0 + ai * HALF + m * 16) * 1024 + col0 + bj * HALF;
;                         f32x4 v0 = acc[ai][bj][m][0] + b0, v1 = acc[ai][bj][m][1] + b1;
;                         if (kind == 0) {
; #pragma unroll
;                             for (int i = 0; i < 4; ++i) { float z = -v0[i]; float sp = fmaxf(z, 0.f) + __logf(1.0f + __expf(-fabsf(z))); v0[i] = __expf(-__expf(-sp - 0.5f));
;                                                           z = -v1[i]; sp = fmaxf(z, 0.f) + __logf(1.0f + __expf(-fabsf(z))); v1[i] = __expf(-__expf(-sp - 0.5f)); }
;                             *(f32x4*)(DEC + off) = v0; *(f32x4*)(DEC + off + 4) = v1;
.LBB0_979:
	s_andn2_b64 vcc, exec, s[0:1]
	s_cbranch_vccnz .LBB0_981
	v_lshl_add_u64 v[158:159], v[158:159], 2, s[36:37]
	v_mul_f32_e32 v168, 0xbfb8aa3b, v168
	v_mul_f32_e32 v169, 0xbfb8aa3b, v169
	v_mul_f32_e32 v170, 0xbfb8aa3b, v164
	v_mul_f32_e32 v171, 0xbfb8aa3b, v165
	v_mul_f32_e32 v176, 0xbfb8aa3b, v166
	v_mul_f32_e32 v177, 0xbfb8aa3b, v167
	v_mul_f32_e32 v178, 0xbfb8aa3b, v162
	v_mul_f32_e32 v179, 0xbfb8aa3b, v163
	v_exp_f32_e32 v168, v168
	v_exp_f32_e32 v169, v169
	v_exp_f32_e32 v170, v170
	v_exp_f32_e32 v171, v171
	v_exp_f32_e32 v176, v176
	v_exp_f32_e32 v177, v177
	v_exp_f32_e32 v178, v178
	v_exp_f32_e32 v179, v179
	v_add_f32_e32 v168, 1.0, v168
	v_add_f32_e32 v169, 1.0, v169
	v_add_f32_e32 v170, 1.0, v170
	v_add_f32_e32 v171, 1.0, v171
	v_add_f32_e32 v176, 1.0, v176
	v_add_f32_e32 v177, 1.0, v177
	v_add_f32_e32 v178, 1.0, v178
	v_add_f32_e32 v179, 1.0, v179
	v_rcp_f32_e32 v168, v168
	v_rcp_f32_e32 v169, v169
	v_rcp_f32_e32 v170, v170
	v_rcp_f32_e32 v171, v171
	v_rcp_f32_e32 v176, v176
	v_rcp_f32_e32 v177, v177
	v_rcp_f32_e32 v178, v178
	v_rcp_f32_e32 v179, v179
	v_mul_f32_e32 v168, 0xbf60028b, v168
	v_mul_f32_e32 v169, 0xbf60028b, v169
	v_mul_f32_e32 v170, 0xbf60028b, v170
	v_mul_f32_e32 v171, 0xbf60028b, v171
	v_mul_f32_e32 v176, 0xbf60028b, v176
	v_mul_f32_e32 v177, 0xbf60028b, v177
	v_mul_f32_e32 v178, 0xbf60028b, v178
	v_mul_f32_e32 v179, 0xbf60028b, v179
	v_exp_f32_e32 v168, v168
	v_exp_f32_e32 v169, v169
	v_exp_f32_e32 v170, v170
	v_exp_f32_e32 v171, v171
	v_exp_f32_e32 v176, v176
	v_exp_f32_e32 v177, v177
	v_exp_f32_e32 v178, v178
	v_exp_f32_e32 v179, v179
	s_nop 0
	global_store_dwordx4 v[158:159], v[168:171], off
	global_store_dwordx4 v[158:159], v[176:179], off offset:16

;     __device__ __forceinline__ void operator()(f32x4 (&acc)[2][2][4][2], const Unit& u, int wr, int wc, int fr_, int fq_) const {
;     ...
;                     for (int m = 0; m < 4; ++m) { const size_t off = (size_t)(row0 + ai * HALF + m * 16) * 1024 + col0 + bj * HALF;
;                         f32x4 v0 = acc[ai][bj][m][0] + b0, v1 = acc[ai][bj][m][1] + b1;
;                         if (kind == 0) {
; #pragma unroll
;                             for (int i = 0; i < 4; ++i) { float z = -v0[i]; float sp = fmaxf(z, 0.f) + __logf(1.0f + __expf(-fabsf(z))); v0[i] = __expf(-__expf(-sp - 0.5f));
;                                                           z = -v1[i]; sp = fmaxf(z, 0.f) + __logf(1.0f + __expf(-fabsf(z))); v1[i] = __expf(-__expf(-sp - 0.5f)); }
;                             *(f32x4*)(DEC + off) = v0; *(f32x4*)(DEC + off + 4) = v1;
.LBB0_987:
	s_andn2_b64 vcc, exec, s[0:1]
	s_cbranch_vccnz .LBB0_989
	v_lshl_add_u64 v[158:159], v[158:159], 2, s[36:37]
	v_mul_f32_e32 v132, 0xbfb8aa3b, v132
	v_mul_f32_e32 v133, 0xbfb8aa3b, v133
	v_mul_f32_e32 v134, 0xbfb8aa3b, v134
	v_mul_f32_e32 v135, 0xbfb8aa3b, v135
	v_mul_f32_e32 v128, 0xbfb8aa3b, v128
	v_mul_f32_e32 v129, 0xbfb8aa3b, v129
	v_mul_f32_e32 v130, 0xbfb8aa3b, v130
	v_mul_f32_e32 v131, 0xbfb8aa3b, v131
	v_exp_f32_e32 v132, v132
	v_exp_f32_e32 v133, v133
	v_exp_f32_e32 v134, v134
	v_exp_f32_e32 v135, v135
	v_exp_f32_e32 v128, v128
	v_exp_f32_e32 v129, v129
	v_exp_f32_e32 v130, v130
	v_exp_f32_e32 v131, v131
	v_add_f32_e32 v132, 1.0, v132
	v_add_f32_e32 v133, 1.0, v133
	v_add_f32_e32 v134, 1.0, v134
	v_add_f32_e32 v135, 1.0, v135
	v_add_f32_e32 v128, 1.0, v128
	v_add_f32_e32 v129, 1.0, v129
	v_add_f32_e32 v130, 1.0, v130
	v_add_f32_e32 v131, 1.0, v131
	v_rcp_f32_e32 v132, v132
	v_rcp_f32_e32 v133, v133
	v_rcp_f32_e32 v134, v134
	v_rcp_f32_e32 v135, v135
	v_rcp_f32_e32 v128, v128
	v_rcp_f32_e32 v129, v129
	v_rcp_f32_e32 v130, v130
	v_rcp_f32_e32 v131, v131
	v_mul_f32_e32 v132, 0xbf60028b, v132
	v_mul_f32_e32 v133, 0xbf60028b, v133
	v_mul_f32_e32 v134, 0xbf60028b, v134
	v_mul_f32_e32 v135, 0xbf60028b, v135
	v_mul_f32_e32 v128, 0xbf60028b, v128
	v_mul_f32_e32 v129, 0xbf60028b, v129
	v_mul_f32_e32 v130, 0xbf60028b, v130
	v_mul_f32_e32 v131, 0xbf60028b, v131
	v_exp_f32_e32 v132, v132
	v_exp_f32_e32 v133, v133
	v_exp_f32_e32 v134, v134
	v_exp_f32_e32 v135, v135
	v_exp_f32_e32 v128, v128
	v_exp_f32_e32 v129, v129
	v_exp_f32_e32 v130, v130
	v_exp_f32_e32 v131, v131
	s_nop 0
	global_store_dwordx4 v[158:159], v[132:135], off
	global_store_dwordx4 v[158:159], v[128:131], off offset:16
